# longest-first attention queue plus next unit index requested one unit ahead (atomic round trip hidden behind the current unit)
# baseline (speedup 1.0000x reference)
.LBB0_797:
	s_waitcnt vmcnt(0)
	v_readfirstlane_b32 s43, v255
	s_and_saveexec_b64 s[12:13], s[10:11]
	v_mov_b32_e32 v255, 1
	s_nop 0
	global_atomic_add v255, v183, v255, s[38:39] offset:4 sc0
	s_or_b64 exec, exec, s[12:13]
	s_cmpk_gt_i32 s43, 0x3fff
	s_mov_b64 s[12:13], -1
	s_cbranch_scc1 .LBB0_796
	s_cmpk_lt_u32 s43, 0x3800
	s_cbranch_scc0 .Lq_tail
	s_mul_hi_u32 s12, s43, 0x4924925
	s_mul_i32 s13, s12, 56
	s_sub_i32 s13, s43, s13
	s_add_i32 s13, s13, 8
	s_lshl_b32 s12, s12, 6
	s_or_b32 s43, s12, s13
	s_branch .Lq_mapped
